# NA item tail waits vmcnt(7) (stores only) and phase-B item start vmcnt(4): no waiting on the previous item's store acks
# baseline (speedup 1.0000x reference)
.LBB0_624:
	v_lshlrev_b32_e32 v0, 1, v166
	s_cmp_lt_i32 s7, 0
	v_lshl_add_u64 v[6:7], v[48:49], 0, v[0:1]
	s_cselect_b64 s[4:5], -1, 0
	s_waitcnt vmcnt(7) lgkmcnt(0)
	v_mov_b32_e32 v99, v147
	v_mov_b32_e32 v98, v146
	v_mov_b32_e32 v97, v145
	v_mov_b32_e32 v96, v144
	v_mov_b32_e32 v103, v143
	v_mov_b32_e32 v102, v142
	v_mov_b32_e32 v101, v141
	v_mov_b32_e32 v100, v140
	v_mov_b32_e32 v107, v139
	v_mov_b32_e32 v106, v138
	v_mov_b32_e32 v105, v137
	v_mov_b32_e32 v104, v136
	v_mov_b32_e32 v111, v135
	v_mov_b32_e32 v110, v134
	v_mov_b32_e32 v109, v133
	v_mov_b32_e32 v108, v132
	v_mov_b32_e32 v115, v131
	v_mov_b32_e32 v114, v130
	v_mov_b32_e32 v113, v129
	v_mov_b32_e32 v112, v128
	v_mov_b32_e32 v119, v93
	v_mov_b32_e32 v118, v92
	v_mov_b32_e32 v117, v91
	v_mov_b32_e32 v116, v90
	v_mov_b32_e32 v123, v89
	v_mov_b32_e32 v122, v88
	v_mov_b32_e32 v121, v87
	v_mov_b32_e32 v120, v86
	v_mov_b32_e32 v127, v85
	v_mov_b32_e32 v126, v84
	v_mov_b32_e32 v125, v83
	v_mov_b32_e32 v124, v82
	global_store_dwordx4 v[6:7], v[2:5], off offset:128
	s_branch .LBB0_348

.LBB0_679:
	s_or_b64 exec, exec, s[4:5]
	s_mov_b64 s[10:11], s[40:41]
	s_waitcnt lgkmcnt(0)
	s_barrier
	s_add_u32 s4, s10, 0xd200000
	s_addc_u32 s5, s11, 0
	s_add_u32 s8, s10, 0x13400000
	s_addc_u32 s9, s11, 0
	s_add_u32 s12, s10, 0x1b400000
	s_addc_u32 s13, s11, 0
	v_readlane_b32 s0, v254, 5
	s_add_u32 s0, s12, s0
	v_readlane_b32 s1, v254, 4
	v_mbcnt_lo_u32_b32 v0, -1, 0
	v_mbcnt_hi_u32_b32 v0, -1, v0
	s_addc_u32 s1, s13, s1
	v_add_u32_e32 v6, s69, v0
	v_readlane_b32 s6, v254, 6
	v_readlane_b32 s7, v254, 7
	s_add_u32 s20, s0, s6
	v_bfe_u32 v0, v6, 4, 2
	v_readlane_b32 s0, v252, 52
	s_addc_u32 s21, s1, s7
	v_and_b32_e32 v3, 15, v6
	v_or_b32_e32 v2, s0, v0
	v_lshlrev_b32_e32 v0, 2, v0
	v_readlane_b32 s0, v254, 8
	v_mul_lo_u32 v2, v2, s43
	v_bitop3_b32 v0, v0, v3, s84 bitop3:0x36
	s_add_u32 s0, s20, s0
	v_lshl_or_b32 v118, v0, 4, v2
	v_mov_b32_e32 v119, v1
	s_addc_u32 s1, s21, 0
	v_lshl_add_u64 v[2:3], s[0:1], 0, v[118:119]
	s_mov_b32 s0, 0xfff20000
	s_mov_b32 s1, -1
	v_lshl_add_u64 v[4:5], v[2:3], 0, s[0:1]
	s_mov_b32 s0, 0xfff20600
	s_mov_b32 m0, s85
	s_mov_b32 s1, -1
	global_load_lds_dwordx4 v[4:5], off
	v_lshl_add_u64 v[2:3], v[2:3], 0, s[0:1]
	s_add_i32 m0, s85, 0x2000
	v_readlane_b32 s0, v254, 9
	s_add_u32 s0, s20, s0
	s_addc_u32 s1, s21, 0
	global_load_lds_dwordx4 v[2:3], off
	v_lshl_add_u64 v[2:3], s[0:1], 0, v[118:119]
	s_mov_b32 s0, 0xfff90000
	s_mov_b32 s1, -1
	v_lshl_add_u64 v[4:5], v[2:3], 0, s[0:1]
	s_mov_b32 s0, 0xfff90600
	s_add_i32 m0, s85, 0x4000
	s_mov_b32 s1, -1
	v_readlane_b32 s50, v254, 11
	global_load_lds_dwordx4 v[4:5], off
	v_lshl_add_u64 v[2:3], v[2:3], 0, s[0:1]
	s_add_i32 m0, s85, 0x6000
	s_mul_i32 s0, s50, 0x3800
	s_add_u32 s0, s20, s0
	s_addc_u32 s1, s21, 0
	global_load_lds_dwordx4 v[2:3], off
	v_lshl_add_u64 v[2:3], s[0:1], 0, v[118:119]
	s_add_i32 m0, s85, 0x8000
	v_lshl_add_u64 v[4:5], v[2:3], 0, s[92:93]
	global_load_lds_dwordx4 v118, s[0:1]
	s_add_i32 m0, s85, 0xa000
	s_mov_b64 s[0:1], 0x70000
	global_load_lds_dwordx4 v[4:5], off
	v_lshl_add_u64 v[4:5], v[2:3], 0, s[0:1]
	s_mov_b64 s[0:1], 0x70600
	v_lshl_add_u64 v[2:3], v[2:3], 0, s[0:1]
	v_and_b32_e32 v7, 31, v6
	v_readlane_b32 s0, v254, 12
	s_add_i32 m0, s85, 0xc000
	v_mov_b32_e32 v121, v1
	v_or_b32_e32 v0, s0, v7
	v_readlane_b32 s0, v253, 14
	global_load_lds_dwordx4 v[4:5], off
	s_add_i32 m0, s85, 0xe000
	v_readlane_b32 s1, v253, 15
	global_load_lds_dwordx4 v[2:3], off
	s_nop 0
	v_lshl_add_u64 v[2:3], s[0:1], 0, v[0:1]
	v_mov_b64_e32 v[4:5], s[12:13]
	v_mad_u64_u32 v[4:5], s[0:1], v2, s43, v[4:5]
	v_readlane_b32 s0, v254, 13
	v_mad_i32_i24 v5, v3, s43, v5
	v_readlane_b32 s1, v254, 14
	v_lshrrev_b32_e32 v0, 1, v6
	s_waitcnt vmcnt(4)
	v_and_b32_e32 v120, 16, v0
	v_lshl_add_u64 v[2:3], v[4:5], 0, s[0:1]
	s_waitcnt lgkmcnt(0)
	s_barrier
	v_lshl_add_u64 v[2:3], v[2:3], 0, v[120:121]
	global_load_dwordx4 v[82:85], v[2:3], off
	global_load_dwordx4 v[86:89], v[2:3], off offset:32
	global_load_dwordx4 v[90:93], v[2:3], off offset:64
	global_load_dwordx4 v[94:97], v[2:3], off offset:96
	global_load_dwordx4 v[98:101], v[2:3], off offset:128
	global_load_dwordx4 v[102:105], v[2:3], off offset:160
	global_load_dwordx4 v[106:109], v[2:3], off offset:192
	global_load_dwordx4 v[110:113], v[2:3], off offset:224
	v_readlane_b32 s0, v253, 4
	v_and_b32_e32 v0, 7, v6
	v_lshlrev_b32_e32 v122, 4, v0
	v_mov_b32_e32 v2, s0
	s_movk_i32 s0, 0x90
	v_bfe_u32 v124, v6, 3, 3
	v_mov_b32_e32 v123, v1
	v_mad_u32_u24 v129, v7, s0, v2
	v_mad_u32_u24 v131, v124, s0, v2
	v_lshl_add_u64 v[4:5], s[10:11], 0, v[122:123]
	s_mov_b64 s[0:1], 0xd400000
	v_lshl_add_u64 v[132:133], v[4:5], 0, s[0:1]
	s_mov_b64 s[0:1], 0x10400000
	v_bfe_u32 v3, v6, 5, 1
	v_lshlrev_b32_e32 v0, 3, v0
	v_lshl_add_u64 v[134:135], v[4:5], 0, s[0:1]
	v_readlane_b32 s0, v254, 32
	v_and_b32_e32 v125, 63, v6
	v_lshlrev_b32_e32 v8, 3, v3
	v_or_b32_e32 v2, 64, v0
	v_lshl_add_u32 v3, v3, 2, s0
	s_mov_b32 s19, 4
	v_or_b32_e32 v127, s31, v7
	v_cmp_gt_u32_e64 s[6:7], 32, v125
	v_or_b32_e32 v126, 8, v124
	v_or_b32_e32 v128, 16, v124
	v_or_b32_e32 v130, 24, v124
	v_add_u32_e32 v217, 0x480, v131
	v_add_u32_e32 v218, 0x900, v131
	v_add_u32_e32 v219, 0xd80, v131
	v_sub_u32_e32 v123, v3, v7
	s_mov_b32 s28, 0
	s_mov_b64 s[24:25], 0
	v_lshlrev_b32_e32 v136, 1, v0
	v_lshlrev_b32_e32 v138, 1, v2
	v_add_u32_e32 v220, v129, v8
	s_mov_b32 s51, 4
	s_mov_b32 s49, s66
	s_mov_b32 s48, 0
	s_mov_b32 s29, s66
	v_and_b32_e32 v240, 31, v125
	v_lshrrev_b32_e32 v241, 5, v125
	v_lshlrev_b32_e32 v242, 2, v125
	v_and_b32_e32 v242, 12, v242
	v_bfe_u32 v243, v125, 2, 2
	v_or_b32_e32 v242, v242, v243
	v_xor_b32_e32 v244, v241, v242
	v_lshlrev_b32_e32 v244, 4, v244
	v_lshl_add_u32 v238, v240, 8, v244
	v_lshl_or_b32 v245, v241, 2, v243
	v_lshlrev_b32_e32 v246, 2, v243
	v_or_b32_e32 v246, v246, v241
	v_bfe_u32 v247, v125, 1, 1
	v_lshrrev_b32_e32 v248, 3, v125
	v_and_or_b32 v247, v248, 2, v247
	v_xor_b32_e32 v247, v247, v246
	v_lshlrev_b32_e32 v247, 4, v247
	v_lshl_add_u32 v247, v245, 8, v247
	v_lshlrev_b32_e32 v248, 3, v125
	v_and_b32_e32 v248, 8, v248
	v_add_u32_e32 v239, v247, v248
	v_add_u32_e32 v239, 0x2000, v239
	s_waitcnt vmcnt(0)
	s_branch .LBB0_681

.LBB0_681:
	s_mul_hi_i32 s0, s29, 0x2aaaaaab
	s_lshr_b32 s1, s0, 31
	s_ashr_i32 s0, s0, 3
	s_add_i32 s10, s0, s1
	s_mul_i32 s0, s10, 48
	s_sub_i32 s11, s29, s0
	v_mov_b32_e32 v14, v1
	v_mov_b32_e32 v15, v1
	s_lshl_b32 s0, s11, 8
	v_mov_b32_e32 v0, v1
	v_mov_b32_e32 v2, v1
	v_mov_b32_e32 v3, v1
	v_mov_b32_e32 v4, v1
	v_mov_b32_e32 v5, v1
	v_mov_b32_e32 v6, v1
	v_mov_b32_e32 v7, v1
	v_mov_b32_e32 v8, v1
	v_mov_b32_e32 v9, v1
	v_mov_b32_e32 v10, v1
	v_mov_b32_e32 v11, v1
	v_mov_b32_e32 v12, v1
	v_mov_b32_e32 v13, v1
	v_mov_b64_e32 v[64:65], v[14:15]
	v_mov_b64_e32 v[48:49], v[14:15]
	v_mov_b64_e32 v[32:33], v[14:15]
	s_and_b32 s52, s0, 0x700
	v_mov_b64_e32 v[62:63], v[12:13]
	v_mov_b64_e32 v[60:61], v[10:11]
	v_mov_b64_e32 v[58:59], v[8:9]
	v_mov_b64_e32 v[56:57], v[6:7]
	v_mov_b64_e32 v[54:55], v[4:5]
	v_mov_b64_e32 v[52:53], v[2:3]
	v_mov_b64_e32 v[50:51], v[0:1]
	v_mov_b64_e32 v[46:47], v[12:13]
	v_mov_b64_e32 v[44:45], v[10:11]
	v_mov_b64_e32 v[42:43], v[8:9]
	v_mov_b64_e32 v[40:41], v[6:7]
	v_mov_b64_e32 v[38:39], v[4:5]
	v_mov_b64_e32 v[36:37], v[2:3]
	v_mov_b64_e32 v[34:35], v[0:1]
	v_mov_b64_e32 v[30:31], v[12:13]
	v_mov_b64_e32 v[28:29], v[10:11]
	v_mov_b64_e32 v[26:27], v[8:9]
	v_mov_b64_e32 v[24:25], v[6:7]
	v_mov_b64_e32 v[22:23], v[4:5]
	v_mov_b64_e32 v[20:21], v[2:3]
	v_mov_b64_e32 v[18:19], v[0:1]
	v_mov_b64_e32 v[16:17], v[14:15]
	s_sub_i32 s26, s52, 64
	v_mov_b32_e32 v115, 0xc61c4000
	v_mov_b32_e32 v114, 0
	s_mov_b32 s27, 0
	s_mov_b64 s[14:15], s[24:25]
	v_mov_b64_e32 v[14:15], v[12:13]
	v_mov_b64_e32 v[12:13], v[10:11]
	v_mov_b64_e32 v[10:11], v[8:9]
	v_mov_b64_e32 v[8:9], v[6:7]
	v_mov_b64_e32 v[6:7], v[4:5]
	v_mov_b64_e32 v[4:5], v[2:3]
	v_mov_b64_e32 v[2:3], v[0:1]
	s_mov_b32 s53, 0
	s_waitcnt vmcnt(4) lgkmcnt(0)
	s_mov_b64 s[24:25], -1
	s_and_b64 vcc, exec, s[14:15]
	s_cbranch_vccnz .LBB0_687
	s_branch .LBB0_683
